# sparse attention softmax: the 16 wave reductions as DPP row reductions instead of ds_bpermute chains (retried now that PV and the QK epilogue are off the VALU)
# speedup vs baseline: 1.0032x; 1.0032x over previous
; #define LAS __attribute__((address_space(3)))
; __device__ __forceinline__ void dsa_unit(int wv, const Args& A, LAS unsigned char* lds, int s, int qt) {
;     ...
;         { float v[4][8]; float m[8];
; #pragma unroll
;             for (int hh = 0; hh < 8; ++hh) m[hh] = -INFINITY;
; #pragma unroll
;             for (int i = 0; i < 4; ++i) { const int e = lane * 4 + i; const h16x8 hv = e < n ? *(const LAS h16x8*)(Pw + e * 8) : (h16x8){0, 0, 0, 0, 0, 0, 0, 0};
; #pragma unroll
;                 for (int j = 0; j < 8; ++j) { v[i][j] = e < n ? (float)hv[j] : -INFINITY; m[j] = fmaxf(m[j], v[i][j]); } }
;             float sm[8];
; #pragma unroll
;             for (int hh = 0; hh < 8; ++hh) { m[hh] = wave_max(m[hh]); sm[hh] = 0.f; }
; #pragma unroll
;             for (int i = 0; i < 4; ++i)
; #pragma unroll
;                 for (int j = 0; j < 8; ++j) { const float p = __expf(v[i][j] - m[j]); v[i][j] = p; sm[j] += p; }
; #pragma unroll
;             for (int hh = 0; hh < 8; ++hh) sm[hh] = 1.f / wave_sum(sm[hh]);
.Lqk_done:
.LBB0_1458:
	v_cmp_gt_i32_e64 s[18:19], s29, v95
	v_mov_b32_e32 v10, 0
	v_mov_b32_e32 v14, 0
	v_mov_b32_e32 v15, 0
	v_mov_b32_e32 v16, 0
	v_mov_b32_e32 v17, 0
	s_and_saveexec_b64 s[12:13], s[18:19]
	v_add_u32_e32 v0, s28, v96
	ds_read_b128 v[14:17], v0
	s_or_b64 exec, exec, s[12:13]
	v_cmp_gt_i32_e64 s[16:17], s29, v97
	v_mov_b32_e32 v11, 0
	v_mov_b32_e32 v12, 0
	v_mov_b32_e32 v13, 0
	s_and_saveexec_b64 s[12:13], s[16:17]
	v_add_u32_e32 v0, s28, v98
	ds_read_b128 v[10:13], v0
	s_or_b64 exec, exec, s[12:13]
	v_cmp_gt_i32_e64 s[14:15], s29, v99
	v_mov_b32_e32 v2, 0
	v_mov_b32_e32 v6, 0
	v_mov_b32_e32 v7, 0
	v_mov_b32_e32 v8, 0
	v_mov_b32_e32 v9, 0
	s_and_saveexec_b64 s[12:13], s[14:15]
	v_add_u32_e32 v0, s28, v100
	ds_read_b128 v[6:9], v0
	s_or_b64 exec, exec, s[12:13]
	v_cmp_gt_i32_e64 s[12:13], s29, v101
	v_mov_b32_e32 v3, 0
	v_mov_b32_e32 v4, 0
	v_mov_b32_e32 v5, 0
	s_and_saveexec_b64 s[26:27], s[12:13]
	v_add_u32_e32 v0, s28, v102
	ds_read_b128 v[2:5], v0
	s_or_b64 exec, exec, s[26:27]
	s_waitcnt lgkmcnt(0)
	v_cvt_f32_f16_e32 v39, v6
	v_cvt_f32_f16_sdwa v6, v6 dst_sel:DWORD dst_unused:UNUSED_PAD src0_sel:WORD_1
	v_cvt_f32_f16_e32 v0, v14
	v_cvt_f32_f16_e32 v21, v10
	v_cndmask_b32_e64 v39, v151, v39, s[14:15]
	v_cndmask_b32_e64 v40, v151, v6, s[14:15]
	v_cvt_f32_f16_e32 v6, v7
	v_cndmask_b32_e64 v0, v151, v0, s[18:19]
	v_cndmask_b32_e64 v21, v151, v21, s[16:17]
	v_max3_f32 v44, v0, s53, v21
	v_cndmask_b32_e64 v42, v151, v6, s[14:15]
	v_cvt_f32_f16_sdwa v6, v7 dst_sel:DWORD dst_unused:UNUSED_PAD src0_sel:WORD_1
	v_cvt_f32_f16_sdwa v14, v14 dst_sel:DWORD dst_unused:UNUSED_PAD src0_sel:WORD_1
	v_cvt_f32_f16_sdwa v10, v10 dst_sel:DWORD dst_unused:UNUSED_PAD src0_sel:WORD_1
	v_cvt_f32_f16_e32 v18, v15
	v_cndmask_b32_e64 v43, v151, v6, s[14:15]
	v_cvt_f32_f16_e32 v6, v8
	v_cndmask_b32_e64 v14, v151, v14, s[18:19]
	v_cndmask_b32_e64 v32, v151, v10, s[16:17]
	v_max3_f32 v10, v14, s53, v32
	v_cndmask_b32_e64 v46, v151, v6, s[14:15]
	v_cvt_f32_f16_sdwa v6, v8 dst_sel:DWORD dst_unused:UNUSED_PAD src0_sel:WORD_1
	v_cvt_f32_f16_e32 v33, v11
	v_cndmask_b32_e64 v18, v151, v18, s[18:19]
	v_cvt_f32_f16_sdwa v15, v15 dst_sel:DWORD dst_unused:UNUSED_PAD src0_sel:WORD_1
	v_cndmask_b32_e64 v52, v151, v6, s[14:15]
	v_cvt_f32_f16_e32 v6, v9
	v_cndmask_b32_e64 v33, v151, v33, s[16:17]
	v_max3_f32 v45, v18, s53, v33
	v_cvt_f32_f16_sdwa v11, v11 dst_sel:DWORD dst_unused:UNUSED_PAD src0_sel:WORD_1
	v_cndmask_b32_e64 v53, v151, v6, s[14:15]
	v_cvt_f32_f16_sdwa v6, v9 dst_sel:DWORD dst_unused:UNUSED_PAD src0_sel:WORD_1
	v_cndmask_b32_e64 v15, v151, v15, s[18:19]
	v_cndmask_b32_e64 v34, v151, v11, s[16:17]
	v_max3_f32 v11, v15, s53, v34
	v_cndmask_b32_e64 v54, v151, v6, s[14:15]
	v_cvt_f32_f16_e32 v6, v2
	v_cvt_f32_f16_sdwa v2, v2 dst_sel:DWORD dst_unused:UNUSED_PAD src0_sel:WORD_1
	v_cvt_f32_f16_e32 v19, v16
	v_cvt_f32_f16_e32 v35, v12
	v_cndmask_b32_e64 v41, v151, v6, s[12:13]
	v_cndmask_b32_e64 v47, v151, v2, s[12:13]
	v_cvt_f32_f16_e32 v2, v3
	v_max3_f32 v6, v44, v39, v41
	v_max3_f32 v7, v10, v40, v47
	v_cndmask_b32_e64 v19, v151, v19, s[18:19]
	v_cndmask_b32_e64 v55, v151, v2, s[12:13]
	v_cvt_f32_f16_sdwa v2, v3 dst_sel:DWORD dst_unused:UNUSED_PAD src0_sel:WORD_1
	v_max3_f32 v8, v45, v42, v55
	v_cndmask_b32_e64 v35, v151, v35, s[16:17]
	v_max3_f32 v48, v19, s53, v35
	v_cndmask_b32_e64 v56, v151, v2, s[12:13]
	v_cvt_f32_f16_e32 v2, v4
	v_max3_f32 v9, v11, v43, v56
	v_cvt_f32_f16_sdwa v16, v16 dst_sel:DWORD dst_unused:UNUSED_PAD src0_sel:WORD_1
	v_cvt_f32_f16_sdwa v12, v12 dst_sel:DWORD dst_unused:UNUSED_PAD src0_sel:WORD_1
	v_cndmask_b32_e64 v57, v151, v2, s[12:13]
	v_cvt_f32_f16_sdwa v2, v4 dst_sel:DWORD dst_unused:UNUSED_PAD src0_sel:WORD_1
	v_max3_f32 v10, v48, v46, v57
	v_cndmask_b32_e64 v16, v151, v16, s[18:19]
	v_cndmask_b32_e64 v36, v151, v12, s[16:17]
	v_cndmask_b32_e64 v58, v151, v2, s[12:13]
	v_cvt_f32_f16_e32 v2, v5
	v_max3_f32 v12, v16, s53, v36
	v_max3_f32 v4, v12, v52, v58
	v_cvt_f32_f16_e32 v20, v17
	v_cndmask_b32_e64 v59, v151, v2, s[12:13]
	v_cvt_f32_f16_sdwa v2, v5 dst_sel:DWORD dst_unused:UNUSED_PAD src0_sel:WORD_1
	v_mov_b32_e32 v177, v6
	v_cvt_f32_f16_e32 v37, v13
	v_cndmask_b32_e64 v20, v151, v20, s[18:19]
	v_cvt_f32_f16_sdwa v17, v17 dst_sel:DWORD dst_unused:UNUSED_PAD src0_sel:WORD_1
	v_cvt_f32_f16_sdwa v13, v13 dst_sel:DWORD dst_unused:UNUSED_PAD src0_sel:WORD_1
	v_cndmask_b32_e64 v37, v151, v37, s[16:17]
	v_max3_f32 v49, v20, s53, v37
	v_max3_f32 v3, v49, v53, v59
	v_cndmask_b32_e64 v17, v151, v17, s[18:19]
	v_cndmask_b32_e64 v38, v151, v13, s[16:17]
	v_max3_f32 v13, v17, s53, v38
	v_cndmask_b32_e64 v60, v151, v2, s[12:13]
	v_max3_f32 v2, v13, v54, v60
	s_nop 1
	v_max_f32_dpp v177, v177, v177 row_shr:1 row_mask:0xf bank_mask:0xf
	s_nop 1
	v_max_f32_dpp v177, v177, v177 row_shr:2 row_mask:0xf bank_mask:0xf
	s_nop 1
	v_max_f32_dpp v177, v177, v177 row_shr:4 row_mask:0xf bank_mask:0xf
	s_nop 1
	v_max_f32_dpp v177, v177, v177 row_shr:8 row_mask:0xf bank_mask:0xf
	s_nop 1
	v_max_f32_dpp v177, v177, v177 row_bcast:15 row_mask:0xa bank_mask:0xf
	s_nop 1
	v_max_f32_dpp v177, v177, v177 row_bcast:31 row_mask:0xc bank_mask:0xf
	s_nop 0
	v_readlane_b32 s32, v177, 63
	s_nop 1
	v_mov_b32_e32 v61, s32
	v_mov_b32_e32 v178, v7
	v_sub_f32_e32 v0, v0, v61
	v_mul_f32_e32 v0, 0x3fb8aa3b, v0
	s_nop 1
	v_max_f32_dpp v178, v178, v178 row_shr:1 row_mask:0xf bank_mask:0xf
	s_nop 1
	v_max_f32_dpp v178, v178, v178 row_shr:2 row_mask:0xf bank_mask:0xf
	s_nop 1
	v_max_f32_dpp v178, v178, v178 row_shr:4 row_mask:0xf bank_mask:0xf
	s_nop 1
	v_max_f32_dpp v178, v178, v178 row_shr:8 row_mask:0xf bank_mask:0xf
	s_nop 1
	v_max_f32_dpp v178, v178, v178 row_bcast:15 row_mask:0xa bank_mask:0xf
; __device__ __forceinline__ void dsa_unit(int wv, const Args& A, LAS unsigned char* lds, int s, int qt) {
;     ...
;             for (int hh = 0; hh < 8; ++hh) { m[hh] = wave_max(m[hh]); sm[hh] = 0.f; }
; #pragma unroll
;             for (int i = 0; i < 4; ++i)
; #pragma unroll
;                 for (int j = 0; j < 8; ++j) { const float p = __expf(v[i][j] - m[j]); v[i][j] = p; sm[j] += p; }
	s_nop 1
	v_max_f32_dpp v178, v178, v178 row_bcast:31 row_mask:0xc bank_mask:0xf
	s_nop 0
	v_readlane_b32 s32, v178, 63
	s_nop 1
	v_mov_b32_e32 v62, s32
	v_mov_b32_e32 v179, v8
	s_nop 1
	v_max_f32_dpp v179, v179, v179 row_shr:1 row_mask:0xf bank_mask:0xf
	s_nop 1
	v_max_f32_dpp v179, v179, v179 row_shr:2 row_mask:0xf bank_mask:0xf
	s_nop 1
	v_max_f32_dpp v179, v179, v179 row_shr:4 row_mask:0xf bank_mask:0xf
	s_nop 1
	v_max_f32_dpp v179, v179, v179 row_shr:8 row_mask:0xf bank_mask:0xf
	s_nop 1
	v_max_f32_dpp v179, v179, v179 row_bcast:15 row_mask:0xa bank_mask:0xf
	s_nop 1
	v_max_f32_dpp v179, v179, v179 row_bcast:31 row_mask:0xc bank_mask:0xf
	s_nop 0
	v_readlane_b32 s32, v179, 63
	s_nop 1
	v_mov_b32_e32 v63, s32
	v_mov_b32_e32 v180, v9
	s_nop 1
	v_max_f32_dpp v180, v180, v180 row_shr:1 row_mask:0xf bank_mask:0xf
	s_nop 1
	v_max_f32_dpp v180, v180, v180 row_shr:2 row_mask:0xf bank_mask:0xf
	s_nop 1
	v_max_f32_dpp v180, v180, v180 row_shr:4 row_mask:0xf bank_mask:0xf
	s_nop 1
	v_max_f32_dpp v180, v180, v180 row_shr:8 row_mask:0xf bank_mask:0xf
	s_nop 1
	v_max_f32_dpp v180, v180, v180 row_bcast:15 row_mask:0xa bank_mask:0xf
	s_nop 1
	v_max_f32_dpp v180, v180, v180 row_bcast:31 row_mask:0xc bank_mask:0xf
	s_nop 0
	v_readlane_b32 s32, v180, 63
	s_nop 1
	v_mov_b32_e32 v64, s32
	v_mov_b32_e32 v181, v10
	v_exp_f32_e32 v10, v0
	v_sub_f32_e32 v0, v14, v62
	v_mul_f32_e32 v0, 0x3fb8aa3b, v0
	v_exp_f32_e32 v11, v0
	v_sub_f32_e32 v0, v18, v63
	v_mul_f32_e32 v0, 0x3fb8aa3b, v0
	v_exp_f32_e32 v8, v0
	v_sub_f32_e32 v0, v15, v64
	v_mul_f32_e32 v0, 0x3fb8aa3b, v0
	v_exp_f32_e32 v9, v0
	v_pk_add_f32 v[12:13], v[10:11], 0 op_sel_hi:[1,0]
	v_pk_add_f32 v[14:15], v[8:9], 0 op_sel_hi:[1,0]
	s_nop 1
	v_max_f32_dpp v181, v181, v181 row_shr:1 row_mask:0xf bank_mask:0xf
	s_nop 1
	v_max_f32_dpp v181, v181, v181 row_shr:2 row_mask:0xf bank_mask:0xf
	s_nop 1
	v_max_f32_dpp v181, v181, v181 row_shr:4 row_mask:0xf bank_mask:0xf
	s_nop 1
	v_max_f32_dpp v181, v181, v181 row_shr:8 row_mask:0xf bank_mask:0xf
	s_nop 1
	v_max_f32_dpp v181, v181, v181 row_bcast:15 row_mask:0xa bank_mask:0xf
	s_nop 1
	v_max_f32_dpp v181, v181, v181 row_bcast:31 row_mask:0xc bank_mask:0xf
	s_nop 0
	v_readlane_b32 s32, v181, 63
	s_nop 1
	v_mov_b32_e32 v65, s32
	v_mov_b32_e32 v182, v4
	v_sub_f32_e32 v0, v19, v65
	v_mul_f32_e32 v0, 0x3fb8aa3b, v0
	v_exp_f32_e32 v6, v0
	s_nop 1
	v_max_f32_dpp v182, v182, v182 row_shr:1 row_mask:0xf bank_mask:0xf
	s_nop 1
	v_max_f32_dpp v182, v182, v182 row_shr:2 row_mask:0xf bank_mask:0xf
	s_nop 1
	v_max_f32_dpp v182, v182, v182 row_shr:4 row_mask:0xf bank_mask:0xf
	s_nop 1
	v_max_f32_dpp v182, v182, v182 row_shr:8 row_mask:0xf bank_mask:0xf
	s_nop 1
	v_max_f32_dpp v182, v182, v182 row_bcast:15 row_mask:0xa bank_mask:0xf
	s_nop 1
	v_max_f32_dpp v182, v182, v182 row_bcast:31 row_mask:0xc bank_mask:0xf
	s_nop 0
	v_readlane_b32 s32, v182, 63
	s_nop 1
	v_mov_b32_e32 v68, s32
	v_mov_b32_e32 v183, v3
	v_sub_f32_e32 v0, v16, v68
	v_mul_f32_e32 v0, 0x3fb8aa3b, v0
	v_exp_f32_e32 v7, v0
	s_nop 1
	v_max_f32_dpp v183, v183, v183 row_shr:1 row_mask:0xf bank_mask:0xf
	s_nop 1
	v_max_f32_dpp v183, v183, v183 row_shr:2 row_mask:0xf bank_mask:0xf
	s_nop 1
	v_max_f32_dpp v183, v183, v183 row_shr:4 row_mask:0xf bank_mask:0xf
	s_nop 1
	v_max_f32_dpp v183, v183, v183 row_shr:8 row_mask:0xf bank_mask:0xf
	s_nop 1
	v_max_f32_dpp v183, v183, v183 row_bcast:15 row_mask:0xa bank_mask:0xf
	s_nop 1
	v_max_f32_dpp v183, v183, v183 row_bcast:31 row_mask:0xc bank_mask:0xf
	s_nop 0
	v_readlane_b32 s32, v183, 63
	s_nop 1
	v_mov_b32_e32 v69, s32
	v_mov_b32_e32 v184, v2
	v_sub_f32_e32 v0, v20, v69
	v_mul_f32_e32 v0, 0x3fb8aa3b, v0
	v_exp_f32_e32 v4, v0
	s_nop 1
	v_max_f32_dpp v184, v184, v184 row_shr:1 row_mask:0xf bank_mask:0xf
	s_nop 1
	v_max_f32_dpp v184, v184, v184 row_shr:2 row_mask:0xf bank_mask:0xf
	s_nop 1
	v_max_f32_dpp v184, v184, v184 row_shr:4 row_mask:0xf bank_mask:0xf
	s_nop 1
	v_max_f32_dpp v184, v184, v184 row_shr:8 row_mask:0xf bank_mask:0xf
	s_nop 1
	v_max_f32_dpp v184, v184, v184 row_bcast:15 row_mask:0xa bank_mask:0xf
	s_nop 1
	v_max_f32_dpp v184, v184, v184 row_bcast:31 row_mask:0xc bank_mask:0xf
	s_nop 0
	v_readlane_b32 s32, v184, 63
	s_nop 1
	v_mov_b32_e32 v70, s32
	v_sub_f32_e32 v0, v17, v70
	v_mul_f32_e32 v0, 0x3fb8aa3b, v0
	v_exp_f32_e32 v5, v0
	v_sub_f32_e32 v0, v21, v61
	v_mul_f32_e32 v0, 0x3fb8aa3b, v0
	v_exp_f32_e32 v2, v0
	v_sub_f32_e32 v0, v32, v62
	v_mul_f32_e32 v0, 0x3fb8aa3b, v0
	v_exp_f32_e32 v3, v0
	v_sub_f32_e32 v0, v33, v63
	v_mul_f32_e32 v0, 0x3fb8aa3b, v0
	v_pk_add_f32 v[16:17], v[6:7], 0 op_sel_hi:[1,0]
	v_pk_add_f32 v[66:67], v[2:3], v[12:13]
	v_exp_f32_e32 v12, v0
	v_sub_f32_e32 v0, v34, v64
	v_mul_f32_e32 v0, 0x3fb8aa3b, v0
	v_exp_f32_e32 v13, v0
	v_sub_f32_e32 v0, v35, v65
	v_mul_f32_e32 v0, 0x3fb8aa3b, v0
	v_pk_add_f32 v[18:19], v[4:5], 0 op_sel_hi:[1,0]
	v_pk_add_f32 v[50:51], v[12:13], v[14:15]
	v_exp_f32_e32 v14, v0
	v_sub_f32_e32 v0, v36, v68
	v_mul_f32_e32 v0, 0x3fb8aa3b, v0
	v_exp_f32_e32 v15, v0
	v_sub_f32_e32 v0, v37, v69
	v_mul_f32_e32 v0, 0x3fb8aa3b, v0
	v_pk_add_f32 v[48:49], v[14:15], v[16:17]
	v_exp_f32_e32 v16, v0
	v_sub_f32_e32 v0, v38, v70
	v_mul_f32_e32 v0, 0x3fb8aa3b, v0
	v_exp_f32_e32 v17, v0
	v_sub_f32_e32 v0, v39, v61
	v_mul_f32_e32 v0, 0x3fb8aa3b, v0
	v_exp_f32_e32 v34, v0
	v_sub_f32_e32 v0, v40, v62
	v_mul_f32_e32 v0, 0x3fb8aa3b, v0
	v_exp_f32_e32 v35, v0
	v_sub_f32_e32 v0, v42, v63
	v_mul_f32_e32 v0, 0x3fb8aa3b, v0
	v_exp_f32_e32 v32, v0
	v_sub_f32_e32 v0, v43, v64
	v_mul_f32_e32 v0, 0x3fb8aa3b, v0
	v_exp_f32_e32 v33, v0
	v_sub_f32_e32 v0, v46, v65
	v_mul_f32_e32 v0, 0x3fb8aa3b, v0
	v_exp_f32_e32 v20, v0
	v_sub_f32_e32 v0, v52, v68
; __device__ __forceinline__ void dsa_unit(int wv, const Args& A, LAS unsigned char* lds, int s, int qt) {
;     ...
;                 for (int j = 0; j < 8; ++j) { const float p = __expf(v[i][j] - m[j]); v[i][j] = p; sm[j] += p; }
; #pragma unroll
;             for (int hh = 0; hh < 8; ++hh) sm[hh] = 1.f / wave_sum(sm[hh]);
	v_mul_f32_e32 v0, 0x3fb8aa3b, v0
	v_exp_f32_e32 v21, v0
	v_sub_f32_e32 v0, v53, v69
	v_mul_f32_e32 v0, 0x3fb8aa3b, v0
	v_pk_add_f32 v[44:45], v[16:17], v[18:19]
	v_exp_f32_e32 v18, v0
	v_sub_f32_e32 v0, v54, v70
	v_mul_f32_e32 v0, 0x3fb8aa3b, v0
	v_exp_f32_e32 v19, v0
	v_sub_f32_e32 v0, v41, v61
	v_mul_f32_e32 v0, 0x3fb8aa3b, v0
	v_exp_f32_e32 v36, v0
	v_sub_f32_e32 v0, v47, v62
	v_mul_f32_e32 v0, 0x3fb8aa3b, v0
	v_exp_f32_e32 v37, v0
	v_pk_add_f32 v[46:47], v[34:35], v[66:67]
	v_sub_f32_e32 v0, v55, v63
	v_mul_f32_e32 v0, 0x3fb8aa3b, v0
	v_pk_add_f32 v[46:47], v[36:37], v[46:47]
	v_mov_b32_e32 v185, v46
	v_mov_b32_e32 v186, v47
	v_exp_f32_e32 v38, v0
	v_sub_f32_e32 v0, v56, v64
	v_mul_f32_e32 v0, 0x3fb8aa3b, v0
	v_exp_f32_e32 v39, v0
	v_sub_f32_e32 v0, v57, v65
	v_mul_f32_e32 v0, 0x3fb8aa3b, v0
	v_exp_f32_e32 v40, v0
	v_sub_f32_e32 v0, v58, v68
	v_mul_f32_e32 v0, 0x3fb8aa3b, v0
	v_exp_f32_e32 v41, v0
	v_sub_f32_e32 v0, v59, v69
	v_mul_f32_e32 v0, 0x3fb8aa3b, v0
	v_exp_f32_e32 v42, v0
	v_sub_f32_e32 v0, v60, v70
	v_mul_f32_e32 v0, 0x3fb8aa3b, v0
	v_exp_f32_e32 v43, v0
	v_pk_add_f32 v[50:51], v[32:33], v[50:51]
	v_pk_add_f32 v[48:49], v[20:21], v[48:49]
	v_pk_add_f32 v[50:51], v[38:39], v[50:51]
	v_pk_add_f32 v[48:49], v[40:41], v[48:49]
	v_pk_add_f32 v[44:45], v[18:19], v[44:45]
	s_nop 1
	v_add_f32_dpp v185, v185, v185 row_shr:1 row_mask:0xf bank_mask:0xf
	s_nop 1
	v_add_f32_dpp v185, v185, v185 row_shr:2 row_mask:0xf bank_mask:0xf
	s_nop 1
	v_add_f32_dpp v185, v185, v185 row_shr:4 row_mask:0xf bank_mask:0xf
	s_nop 1
	v_add_f32_dpp v185, v185, v185 row_shr:8 row_mask:0xf bank_mask:0xf
	s_nop 1
	v_add_f32_dpp v185, v185, v185 row_bcast:15 row_mask:0xa bank_mask:0xf
	s_nop 1
	v_add_f32_dpp v185, v185, v185 row_bcast:31 row_mask:0xc bank_mask:0xf
	s_nop 0
	v_readlane_b32 s32, v185, 63
	s_nop 1
	v_mov_b32_e32 v46, s32
	s_nop 1
	v_add_f32_dpp v186, v186, v186 row_shr:1 row_mask:0xf bank_mask:0xf
	s_nop 1
	v_add_f32_dpp v186, v186, v186 row_shr:2 row_mask:0xf bank_mask:0xf
	s_nop 1
	v_add_f32_dpp v186, v186, v186 row_shr:4 row_mask:0xf bank_mask:0xf
	s_nop 1
	v_add_f32_dpp v186, v186, v186 row_shr:8 row_mask:0xf bank_mask:0xf
	s_nop 1
	v_add_f32_dpp v186, v186, v186 row_bcast:15 row_mask:0xa bank_mask:0xf
	s_nop 1
	v_add_f32_dpp v186, v186, v186 row_bcast:31 row_mask:0xc bank_mask:0xf
	s_nop 0
	v_readlane_b32 s32, v186, 63
	s_nop 1
	v_mov_b32_e32 v47, s32
	s_nop 0
	v_div_scale_f32 v0, s[26:27], v47, v47, 1.0
	v_rcp_f32_e32 v52, v0
	v_pk_add_f32 v[44:45], v[42:43], v[44:45]
	v_fma_f32 v53, -v0, v52, 1.0
	v_fmac_f32_e32 v52, v53, v52
	v_div_scale_f32 v53, vcc, 1.0, v47, 1.0
	v_mul_f32_e32 v54, v53, v52
	v_fma_f32 v55, -v0, v54, v53
	v_fmac_f32_e32 v54, v55, v52
	v_fma_f32 v0, -v0, v54, v53
	v_div_fmas_f32 v0, v0, v52, v54
	v_div_fixup_f32 v47, v0, v47, 1.0
	v_div_scale_f32 v0, s[26:27], v46, v46, 1.0
	v_rcp_f32_e32 v52, v0
	s_nop 0
	v_fma_f32 v53, -v0, v52, 1.0
	v_fmac_f32_e32 v52, v53, v52
	v_div_scale_f32 v53, vcc, 1.0, v46, 1.0
	v_mul_f32_e32 v54, v53, v52
	v_fma_f32 v55, -v0, v54, v53
	v_fmac_f32_e32 v54, v55, v52
	v_fma_f32 v0, -v0, v54, v53
	v_div_fmas_f32 v0, v0, v52, v54
	v_mov_b32_e32 v187, v50
	v_mov_b32_e32 v188, v51
	v_div_fixup_f32 v46, v0, v46, 1.0
	s_nop 1
	v_add_f32_dpp v187, v187, v187 row_shr:1 row_mask:0xf bank_mask:0xf
	s_nop 1
	v_add_f32_dpp v187, v187, v187 row_shr:2 row_mask:0xf bank_mask:0xf
	s_nop 1
	v_add_f32_dpp v187, v187, v187 row_shr:4 row_mask:0xf bank_mask:0xf
	s_nop 1
	v_add_f32_dpp v187, v187, v187 row_shr:8 row_mask:0xf bank_mask:0xf
	s_nop 1
	v_add_f32_dpp v187, v187, v187 row_bcast:15 row_mask:0xa bank_mask:0xf
	s_nop 1
	v_add_f32_dpp v187, v187, v187 row_bcast:31 row_mask:0xc bank_mask:0xf
	s_nop 0
	v_readlane_b32 s32, v187, 63
	s_nop 1
	v_mov_b32_e32 v50, s32
	s_nop 1
	v_add_f32_dpp v188, v188, v188 row_shr:1 row_mask:0xf bank_mask:0xf
	s_nop 1
	v_add_f32_dpp v188, v188, v188 row_shr:2 row_mask:0xf bank_mask:0xf
	s_nop 1
	v_add_f32_dpp v188, v188, v188 row_shr:4 row_mask:0xf bank_mask:0xf
	s_nop 1
	v_add_f32_dpp v188, v188, v188 row_shr:8 row_mask:0xf bank_mask:0xf
	s_nop 1
	v_add_f32_dpp v188, v188, v188 row_bcast:15 row_mask:0xa bank_mask:0xf
	s_nop 1
	v_add_f32_dpp v188, v188, v188 row_bcast:31 row_mask:0xc bank_mask:0xf
	s_nop 0
	v_readlane_b32 s32, v188, 63
	s_nop 1
	v_mov_b32_e32 v51, s32
	s_nop 0
	v_div_scale_f32 v0, s[26:27], v51, v51, 1.0
	v_rcp_f32_e32 v52, v0
	s_nop 0
	v_fma_f32 v53, -v0, v52, 1.0
	v_fmac_f32_e32 v52, v53, v52
	v_div_scale_f32 v53, vcc, 1.0, v51, 1.0
	v_mul_f32_e32 v54, v53, v52
	v_fma_f32 v55, -v0, v54, v53
	v_fmac_f32_e32 v54, v55, v52
	v_fma_f32 v0, -v0, v54, v53
	v_div_fmas_f32 v0, v0, v52, v54
	v_div_fixup_f32 v51, v0, v51, 1.0
	v_div_scale_f32 v0, s[26:27], v50, v50, 1.0
	v_rcp_f32_e32 v52, v0
	s_nop 0
	v_fma_f32 v53, -v0, v52, 1.0
	v_fmac_f32_e32 v52, v53, v52
	v_div_scale_f32 v53, vcc, 1.0, v50, 1.0
	v_mul_f32_e32 v54, v53, v52
; #define LAS __attribute__((address_space(3)))
; __device__ __forceinline__ void dsa_unit(int wv, const Args& A, LAS unsigned char* lds, int s, int qt) {
;     ...
;             for (int hh = 0; hh < 8; ++hh) sm[hh] = 1.f / wave_sum(sm[hh]);
; #pragma unroll
;             for (int i = 0; i < 4; ++i) { const int e = lane * 4 + i;
;                 if (e < n) { h16x8 o;
; #pragma unroll
;                     for (int j = 0; j < 8; ++j) o[j] = (h16)(v[i][j] * sm[j]);
;                     *(LAS h16x8*)(Pw + e * 8) = o; } } }
	v_fma_f32 v55, -v0, v54, v53
	v_fmac_f32_e32 v54, v55, v52
	v_fma_f32 v0, -v0, v54, v53
	v_div_fmas_f32 v0, v0, v52, v54
	v_mov_b32_e32 v189, v48
	v_mov_b32_e32 v190, v49
	v_div_fixup_f32 v50, v0, v50, 1.0
	s_nop 1
	v_add_f32_dpp v189, v189, v189 row_shr:1 row_mask:0xf bank_mask:0xf
	s_nop 1
	v_add_f32_dpp v189, v189, v189 row_shr:2 row_mask:0xf bank_mask:0xf
	s_nop 1
	v_add_f32_dpp v189, v189, v189 row_shr:4 row_mask:0xf bank_mask:0xf
	s_nop 1
	v_add_f32_dpp v189, v189, v189 row_shr:8 row_mask:0xf bank_mask:0xf
	s_nop 1
	v_add_f32_dpp v189, v189, v189 row_bcast:15 row_mask:0xa bank_mask:0xf
	s_nop 1
	v_add_f32_dpp v189, v189, v189 row_bcast:31 row_mask:0xc bank_mask:0xf
	s_nop 0
	v_readlane_b32 s32, v189, 63
	s_nop 1
	v_mov_b32_e32 v48, s32
	s_nop 1
	v_add_f32_dpp v190, v190, v190 row_shr:1 row_mask:0xf bank_mask:0xf
	s_nop 1
	v_add_f32_dpp v190, v190, v190 row_shr:2 row_mask:0xf bank_mask:0xf
	s_nop 1
	v_add_f32_dpp v190, v190, v190 row_shr:4 row_mask:0xf bank_mask:0xf
	s_nop 1
	v_add_f32_dpp v190, v190, v190 row_shr:8 row_mask:0xf bank_mask:0xf
	s_nop 1
	v_add_f32_dpp v190, v190, v190 row_bcast:15 row_mask:0xa bank_mask:0xf
	s_nop 1
	v_add_f32_dpp v190, v190, v190 row_bcast:31 row_mask:0xc bank_mask:0xf
	s_nop 0
	v_readlane_b32 s32, v190, 63
	s_nop 1
	v_mov_b32_e32 v49, s32
	s_nop 0
	v_div_scale_f32 v0, s[26:27], v49, v49, 1.0
	v_rcp_f32_e32 v52, v0
	s_nop 0
	v_fma_f32 v53, -v0, v52, 1.0
	v_fmac_f32_e32 v52, v53, v52
	v_div_scale_f32 v53, vcc, 1.0, v49, 1.0
	v_mul_f32_e32 v54, v53, v52
	v_fma_f32 v55, -v0, v54, v53
	v_fmac_f32_e32 v54, v55, v52
	v_fma_f32 v0, -v0, v54, v53
	v_div_fmas_f32 v0, v0, v52, v54
	v_div_fixup_f32 v49, v0, v49, 1.0
	v_div_scale_f32 v0, s[26:27], v48, v48, 1.0
	v_rcp_f32_e32 v52, v0
	s_nop 0
	v_fma_f32 v53, -v0, v52, 1.0
	v_fmac_f32_e32 v52, v53, v52
	v_div_scale_f32 v53, vcc, 1.0, v48, 1.0
	v_mul_f32_e32 v54, v53, v52
	v_fma_f32 v55, -v0, v54, v53
	v_fmac_f32_e32 v54, v55, v52
	v_fma_f32 v0, -v0, v54, v53
	v_div_fmas_f32 v0, v0, v52, v54
	v_mov_b32_e32 v191, v44
	v_mov_b32_e32 v192, v45
	v_div_fixup_f32 v48, v0, v48, 1.0
	s_nop 1
	v_add_f32_dpp v191, v191, v191 row_shr:1 row_mask:0xf bank_mask:0xf
	s_nop 1
	v_add_f32_dpp v191, v191, v191 row_shr:2 row_mask:0xf bank_mask:0xf
	s_nop 1
	v_add_f32_dpp v191, v191, v191 row_shr:4 row_mask:0xf bank_mask:0xf
	s_nop 1
	v_add_f32_dpp v191, v191, v191 row_shr:8 row_mask:0xf bank_mask:0xf
	s_nop 1
	v_add_f32_dpp v191, v191, v191 row_bcast:15 row_mask:0xa bank_mask:0xf
	s_nop 1
	v_add_f32_dpp v191, v191, v191 row_bcast:31 row_mask:0xc bank_mask:0xf
	s_nop 0
	v_readlane_b32 s32, v191, 63
	s_nop 1
	v_mov_b32_e32 v44, s32
	s_nop 1
	v_add_f32_dpp v192, v192, v192 row_shr:1 row_mask:0xf bank_mask:0xf
	s_nop 1
	v_add_f32_dpp v192, v192, v192 row_shr:2 row_mask:0xf bank_mask:0xf
	s_nop 1
	v_add_f32_dpp v192, v192, v192 row_shr:4 row_mask:0xf bank_mask:0xf
	s_nop 1
	v_add_f32_dpp v192, v192, v192 row_shr:8 row_mask:0xf bank_mask:0xf
	s_nop 1
	v_add_f32_dpp v192, v192, v192 row_bcast:15 row_mask:0xa bank_mask:0xf
	s_nop 1
	v_add_f32_dpp v192, v192, v192 row_bcast:31 row_mask:0xc bank_mask:0xf
	s_nop 0
	v_readlane_b32 s32, v192, 63
	s_nop 1
	v_mov_b32_e32 v45, s32
	s_nop 0
	v_div_scale_f32 v0, s[26:27], v45, v45, 1.0
	v_rcp_f32_e32 v52, v0
	s_nop 0
	v_fma_f32 v53, -v0, v52, 1.0
	v_fmac_f32_e32 v52, v53, v52
	v_div_scale_f32 v53, vcc, 1.0, v45, 1.0
	v_mul_f32_e32 v54, v53, v52
	v_fma_f32 v55, -v0, v54, v53
	v_fmac_f32_e32 v54, v55, v52
	v_fma_f32 v0, -v0, v54, v53
	v_div_fmas_f32 v0, v0, v52, v54
	v_div_fixup_f32 v45, v0, v45, 1.0
	v_div_scale_f32 v0, s[26:27], v44, v44, 1.0
	v_rcp_f32_e32 v52, v0
	s_nop 0
	v_fma_f32 v53, -v0, v52, 1.0
	v_fmac_f32_e32 v52, v53, v52
	v_div_scale_f32 v53, vcc, 1.0, v44, 1.0
	v_mul_f32_e32 v54, v53, v52
	v_fma_f32 v55, -v0, v54, v53
	v_fmac_f32_e32 v54, v55, v52
	v_fma_f32 v0, -v0, v54, v53
	v_div_fmas_f32 v0, v0, v52, v54
	v_div_fixup_f32 v44, v0, v44, 1.0
	s_and_saveexec_b64 s[26:27], s[18:19]
	s_cbranch_execz .LBB0_1473
	v_fma_mixlo_f16 v0, v10, v46, 0
	v_mov_b32_e32 v10, v11
	v_mov_b32_e32 v11, v8
	v_pk_mov_b32 v[52:53], v[46:47], v[50:51] op_sel:[1,0]
	s_nop 0
	v_pk_mul_f32 v[10:11], v[10:11], v[52:53]
	v_pk_mov_b32 v[52:53], v[50:51], v[48:49] op_sel:[1,0]
	v_cvt_pk_f16_f32 v54, v10, v11
	v_mov_b32_e32 v10, v9
	v_mov_b32_e32 v11, v6
	v_pk_mul_f32 v[10:11], v[10:11], v[52:53]
	v_pack_b32_f16 v8, v0, v54
	v_cvt_pk_f16_f32 v0, v10, v11
	v_mov_b32_e32 v6, v7
	v_mov_b32_e32 v7, v4
	v_pk_mov_b32 v[10:11], v[48:49], v[44:45] op_sel:[1,0]
	v_alignbit_b32 v9, v0, v54, 16
	v_pk_mul_f32 v[6:7], v[6:7], v[10:11]
	s_nop 0
	v_cvt_pk_f16_f32 v4, v6, v7
	v_lshrrev_b32_e32 v11, 16, v4
	v_alignbit_b32 v10, v4, v0, 16
	v_fma_mixhi_f16 v11, v5, v45, 0
	v_add_u32_e32 v0, s28, v96
	ds_write_b128 v0, v[8:11]
	s_or_b64 exec, exec, s[26:27]
	s_and_saveexec_b64 s[18:19], s[16:17]
	s_cbranch_execnz .LBB0_1474
